# scan: last-chunk units swapped onto the 8 sample-step workgroups; pass 1 of a last-chunk unit keeps only the K-stream (its summary is never read)
# speedup vs baseline: 1.0091x; 1.0091x over previous
.LBB0_1834:
	s_cmp_le_i32 s74, s8
	s_cselect_b64 s[0:1], -1, 0
	s_cmp_lt_i32 s8, s75
	s_cselect_b64 s[2:3], -1, 0
	s_and_b64 s[0:1], s[0:1], s[2:3]
	s_andn2_b64 vcc, exec, s[0:1]
	s_cbranch_vccnz .LBB0_2049
	v_readlane_b32 s0, v251, 52
	v_mbcnt_lo_u32_b32 v0, -1, 0
	v_mbcnt_hi_u32_b32 v0, -1, v0
	s_mov_b64 s[50:51], s[72:73]
	v_readlane_b32 s52, v251, 1
	s_waitcnt vmcnt(0)
	v_add_u32_e32 v114, s0, v0
	v_readlane_b32 s0, v251, 49
	v_readlane_b32 s1, v251, 50
	s_load_dword s15, s[0:1], 0x0
	s_mov_b64 s[0:1], s[70:71]
	s_add_u32 s30, s50, 0xdd00000
	v_writelane_b32 v254, s0, 55
	s_addc_u32 s34, s51, 0
	v_readfirstlane_b32 s2, v114
	v_writelane_b32 v254, s1, 56
	v_and_b32_e32 v2, 63, v114
	v_readlane_b32 s0, v254, 49
	s_add_i32 s14, s0, 1
	s_lshl_b32 s31, s0, 19
	v_readlane_b32 s1, v254, 50
	s_mov_b32 s6, s0
	s_add_u32 s0, s50, s31
	s_addc_u32 s1, s51, 0
	s_ashr_i32 s5, s2, 2
	v_bfi_b32 v122, -16, s5, v114
	v_ashrrev_i32_e32 v123, 31, v122
	v_lshrrev_b32_e32 v3, 2, v114
	v_and_b32_e32 v163, 48, v3
	v_cmp_gt_u32_e64 s[36:37], 16, v2
	v_cmp_lt_u32_e64 s[38:39], 31, v2
	v_lshl_add_u64 v[2:3], v[122:123], 3, s[0:1]
	s_mov_b64 s[0:1], 0x300000
	s_lshl_b32 s2, s6, 10
	s_waitcnt lgkmcnt(0)
	v_lshlrev_b64 v[0:1], 8, v[122:123]
	v_lshl_add_u64 v[130:131], v[2:3], 0, s[0:1]
	s_add_i32 s0, 0, 0x16000
	v_lshlrev_b32_e32 v123, 4, v114
	v_ashrrev_i32_e32 v115, 31, v114
	v_writelane_b32 v254, s2, 53
	v_lshl_add_u64 v[0:1], s[50:51], 0, v[0:1]
	v_and_b32_e32 v32, 48, v114
	v_add_u32_e32 v227, s0, v123
	v_lshl_add_u64 v[2:3], v[114:115], 4, s[50:51]
	s_mov_b64 s[0:1], 0x24900000
	v_writelane_b32 v254, s3, 54
	v_lshl_add_u64 v[0:1], v[0:1], 0, v[32:33]
	s_mov_b64 s[2:3], 0xc00000
	v_lshl_add_u64 v[132:133], v[2:3], 0, s[0:1]
	s_movk_i32 s0, 0x430
	v_lshl_add_u64 v[124:125], v[0:1], 0, s[2:3]
	v_ashrrev_i32_e32 v0, 7, v114
	s_movk_i32 s2, 0x80
	v_cmp_gt_i32_e64 s[40:41], s0, v114
	s_movk_i32 s0, 0x230
	v_bfe_u32 v162, v114, 4, 2
	v_ashrrev_i32_e32 v1, 31, v0
	v_cmp_gt_i32_e64 s[2:3], s2, v114
	v_lshl_add_u32 v165, v122, 2, 0
	v_add_u32_e32 v115, 0x200, v114
	v_add_u32_e32 v4, 0x400, v114
	v_cmp_gt_i32_e64 s[42:43], s0, v114
	s_movk_i32 s0, 0x840
	v_and_b32_e32 v127, 15, v114
	v_lshlrev_b64 v[0:1], 11, v[0:1]
	v_writelane_b32 v254, s2, 57
	v_min_i32_e32 v2, 0x42f, v114
	v_min_i32_e32 v3, 0x42f, v115
	v_min_i32_e32 v5, 0x42f, v4
	v_mad_u32_u24 v234, v162, s0, v165
	v_readlane_b32 s56, v251, 5
	v_readlane_b32 s57, v251, 6
	v_readlane_b32 s0, v253, 14
	v_writelane_b32 v254, s3, 58
	v_lshl_add_u32 v129, s6, 12, v114
	s_mul_i32 s2, s6, 0xfffff400
	v_lshlrev_b32_e32 v164, 4, v127
	v_add_u32_e32 v226, 0, v32
	v_ashrrev_i32_e32 v228, 4, v2
	v_lshlrev_b32_e32 v2, 3, v2
	v_ashrrev_i32_e32 v229, 4, v3
	v_lshlrev_b32_e32 v3, 3, v3
	v_ashrrev_i32_e32 v230, 4, v5
	v_lshlrev_b32_e32 v5, 3, v5
	v_lshl_add_u64 v[0:1], s[56:57], 0, v[0:1]
	v_and_b32_e32 v32, 0x7f0, v123
	v_readlane_b32 s1, v253, 15
	v_add_u32_e32 v221, s2, v129
	s_add_i32 s2, 0, 0x18000
	v_ashrrev_i32_e32 v223, 4, v114
	v_add_u32_e32 v126, 0, v164
	v_and_b32_e32 v2, 0x78, v2
	v_and_b32_e32 v3, 0x78, v3
	v_and_b32_e32 v5, 0x78, v5
	v_lshl_add_u64 v[134:135], v[0:1], 0, v[32:33]
	v_cndmask_b32_e64 v0, 0, 1, s[0:1]
	s_lshl_b32 s4, s6, 9
	v_lshl_add_u32 v222, v114, 2, s2
	v_lshlrev_b32_e32 v224, 5, v127
	v_and_or_b32 v225, v223, 3, v163
	v_add_u32_e32 v128, v126, v164
	v_lshlrev_b32_e32 v231, 4, v115
	v_cmp_gt_i32_e64 s[44:45], 48, v114
	v_lshlrev_b32_e32 v232, 4, v4
	v_mul_u32_u24_e32 v233, 0x110, v127
	v_add_u32_e32 v235, 0xc800, v234
	v_cmp_ne_u32_e64 s[46:47], 1, v0
	s_andn2_b64 vcc, exec, s[0:1]
	v_lshlrev_b32_e32 v32, 1, v2
	v_lshlrev_b32_e32 v136, 1, v3
	v_lshlrev_b32_e32 v138, 1, v5
	v_readlane_b32 s53, v251, 2
	v_readlane_b32 s54, v251, 3
	v_readlane_b32 s55, v251, 4
	v_readlane_b32 s58, v251, 7
	v_readlane_b32 s59, v251, 8
	v_readlane_b32 s60, v251, 9
	v_readlane_b32 s61, v251, 10
	v_readlane_b32 s62, v251, 11
	v_readlane_b32 s63, v251, 12
	v_readlane_b32 s64, v251, 13
	v_readlane_b32 s65, v251, 14
	v_readlane_b32 s66, v251, 15
	v_readlane_b32 s67, v251, 16
	s_cbranch_vccnz .LBB0_1863
	v_readlane_b32 s0, v254, 53
	v_readlane_b32 s6, v251, 0
	v_readlane_b32 s1, v254, 54
	v_add_u32_e32 v166, s0, v122
	s_cmp_lt_u32 s6, 8
	s_cbranch_scc0 .LpermAa
	s_lshl_b32 s6, s6, 4
	s_or_b32 s6, s6, 15
	s_branch .LpermAd
.LpermAa:
	s_and_b32 s100, s6, 15
	s_cmp_eq_u32 s100, 15
	s_cselect_b32 s100, 1, 0
	s_cmp_lt_u32 s6, 0x80
	s_cselect_b32 s101, 1, 0
	s_and_b32 s100, s100, s101
	s_cmp_lg_u32 s100, 0
	s_cbranch_scc0 .LpermAd
	s_lshr_b32 s6, s6, 4
.LpermAd:
	s_branch .LBB0_1838
.LBB0_1837:
	s_or_b64 exec, exec, s[0:1]
	s_add_i32 s6, s6, s15
	s_cmpk_lt_i32 s6, 0x100
	s_barrier
	s_cbranch_scc0 .LBB0_1863

.LBB0_1853:
	s_or_b64 exec, exec, s[0:1]
	s_add_i32 s0, s3, 1
	s_cmp_lg_u32 s3, 7
	s_cselect_b32 s1, s0, 7
	s_lshl_b32 s3, s1, 6
	s_add_i32 s3, s3, s12
	v_add_u32_e32 v34, s3, v228
	v_add_u32_e32 v36, s3, v229
	v_add_u32_e32 v42, s3, v230
	s_lshr_b32 s3, s1, 2
	s_cmp_eq_u32 s3, 1
	s_cselect_b64 vcc, -1, 0
	s_lshl_b32 s1, s1, 16
	v_cndmask_b32_e32 v51, v117, v143, vcc
	v_cndmask_b32_e32 v50, v116, v142, vcc
	s_and_b32 s8, s1, 0x30000
	v_lshl_add_u64 v[74:75], v[50:51], 0, s[8:9]
	s_movk_i32 s1, 0x2000
	v_add_co_u32_e32 v54, vcc, s1, v74
	s_movk_i32 s1, 0x4000
	s_nop 0
	v_addc_co_u32_e32 v55, vcc, 0, v75, vcc
	v_add_co_u32_e32 v58, vcc, s1, v74
	s_movk_i32 s1, 0x6000
	s_nop 0
	v_addc_co_u32_e32 v59, vcc, 0, v75, vcc
	v_add_co_u32_e32 v62, vcc, s1, v74
	s_mov_b32 s1, 0x8000
	s_nop 0
	v_addc_co_u32_e32 v63, vcc, 0, v75, vcc
	v_add_co_u32_e32 v66, vcc, s1, v74
	s_mov_b32 s1, 0xa000
	s_nop 0
	v_addc_co_u32_e32 v67, vcc, 0, v75, vcc
	v_add_co_u32_e32 v70, vcc, s1, v74
	v_max_i32_e32 v34, 0, v34
	v_max_i32_e32 v36, 0, v36
	v_max_i32_e32 v42, 0, v42
	v_addc_co_u32_e32 v71, vcc, 0, v75, vcc
	v_add_u32_e32 v34, s19, v34
	v_add_u32_e32 v36, s19, v36
	v_add_u32_e32 v42, s19, v42
	v_add_co_u32_e32 v76, vcc, 0xc000, v74
	v_ashrrev_i32_e32 v35, 31, v34
	v_ashrrev_i32_e32 v37, 31, v36
	v_ashrrev_i32_e32 v43, 31, v42
	v_addc_co_u32_e32 v77, vcc, 0, v75, vcc
	v_lshlrev_b64 v[34:35], 11, v[34:35]
	v_lshlrev_b64 v[36:37], 11, v[36:37]
	v_lshlrev_b64 v[42:43], 11, v[42:43]
	v_add_co_u32_e32 v78, vcc, 0xe000, v74
	s_waitcnt lgkmcnt(0)
	s_barrier
	v_lshl_add_u64 v[34:35], v[146:147], 0, v[34:35]
	v_lshl_add_u64 v[38:39], v[148:149], 0, v[36:37]
	v_lshl_add_u64 v[42:43], v[150:151], 0, v[42:43]
	v_addc_co_u32_e32 v79, vcc, 0, v75, vcc
	global_load_dwordx4 v[34:37], v[34:35], off
	s_nop 0
	global_load_dwordx4 v[38:41], v[38:39], off
	s_mov_b32 s1, 0
	global_load_dwordx4 v[42:45], v[42:43], off
	s_nop 0
	global_load_dwordx4 v[50:53], v[74:75], off
	s_nop 0
	global_load_dwordx4 v[54:57], v[54:55], off
	s_nop 0
	global_load_dwordx4 v[58:61], v[58:59], off
	s_nop 0
	global_load_dwordx4 v[62:65], v[62:63], off
	s_nop 0
	global_load_dwordx4 v[66:69], v[66:67], off
	s_nop 0
	global_load_dwordx4 v[70:73], v[70:71], off
	s_nop 0
	global_load_dwordx4 v[74:77], v[76:77], off
	s_nop 0
	global_load_dwordx4 v[78:81], v[78:79], off
	s_mov_b64 s[48:49], -1
	s_cmp_eq_u32 s11, 15
	s_cbranch_scc1 .Lp1skip

.Lp1tail:
	s_waitcnt vmcnt(7)
	v_mov_b64_e32 v[112:113], v[52:53]
	s_waitcnt vmcnt(6)
	v_mov_b64_e32 v[88:89], v[56:57]
	s_waitcnt vmcnt(5)
	v_mov_b64_e32 v[92:93], v[60:61]
	s_waitcnt vmcnt(4)
	v_mov_b64_e32 v[96:97], v[64:65]
	s_waitcnt vmcnt(3)
	v_mov_b64_e32 v[100:101], v[68:69]
	s_waitcnt vmcnt(2)
	v_mov_b64_e32 v[104:105], v[72:73]
	s_waitcnt vmcnt(1)
	v_mov_b64_e32 v[108:109], v[76:77]
	s_waitcnt vmcnt(0)
	v_mov_b64_e32 v[46:47], v[78:79]
	v_mov_b64_e32 v[110:111], v[50:51]
	v_mov_b64_e32 v[86:87], v[54:55]
	v_mov_b64_e32 v[90:91], v[58:59]
	v_mov_b64_e32 v[94:95], v[62:63]
	v_mov_b64_e32 v[98:99], v[66:67]
	v_mov_b64_e32 v[102:103], v[70:71]
	v_mov_b64_e32 v[106:107], v[74:75]
	v_mov_b64_e32 v[48:49], v[80:81]
	v_mov_b32_e32 v137, v152
	s_mov_b32 s3, s0
	s_branch .LBB0_1849
.Lp1skip:
	s_waitcnt vmcnt(11)
	v_pk_add_f32 v[82:83], v[110:111], v[82:83]
	v_pk_add_f32 v[84:85], v[112:113], v[84:85]
	v_pk_add_f32 v[82:83], v[86:87], v[82:83]
	v_pk_add_f32 v[84:85], v[88:89], v[84:85]
	v_pk_add_f32 v[82:83], v[90:91], v[82:83]
	v_pk_add_f32 v[84:85], v[92:93], v[84:85]
	v_pk_add_f32 v[82:83], v[94:95], v[82:83]
	v_pk_add_f32 v[84:85], v[96:97], v[84:85]
	v_pk_add_f32 v[82:83], v[98:99], v[82:83]
	v_add_f32_e64 v84, v100, v84
	v_add_f32_e64 v85, v101, v85
	v_pk_add_f32 v[86:87], v[102:103], v[82:83]
	v_pk_add_f32 v[84:85], v[104:105], v[84:85]
	v_pk_add_f32 v[82:83], v[108:109], v[84:85]
	v_add_f32_e64 v86, v106, v86
	v_add_f32_e64 v87, v107, v87
	s_cmp_eq_u32 s0, 8
	v_pk_add_f32 v[84:85], v[48:49], v[82:83]
	v_pk_add_f32 v[82:83], v[46:47], v[86:87]
	s_cbranch_scc1 .LBB0_1859
	s_branch .Lp1tail

.LBB0_1872:
	s_and_b64 vcc, exec, s[46:47]
	s_cbranch_vccnz .LBB0_1987
	v_readlane_b32 s0, v254, 49
	v_readlane_b32 s1, v254, 50
	v_and_b32_e32 v0, 0xf0, v123
	v_mov_b32_e32 v1, v33
	s_lshl_b32 s35, s0, 1
	v_lshl_add_u64 v[0:1], s[50:51], 0, v[0:1]
	s_cmp_lt_u32 s21, 8
	s_cbranch_scc0 .LpermBa
	s_lshl_b32 s21, s21, 4
	s_or_b32 s21, s21, 15
	s_branch .LpermBd
.LpermBa:
	s_and_b32 s100, s21, 15
	s_cmp_eq_u32 s100, 15
	s_cselect_b32 s100, 1, 0
	s_cmp_lt_u32 s21, 0x80
	s_cselect_b32 s101, 1, 0
	s_and_b32 s100, s100, s101
	s_cmp_lg_u32 s100, 0
	s_cbranch_scc0 .LpermBd
	s_lshr_b32 s21, s21, 4
.LpermBd:
	s_mov_b64 s[0:1], 0xbd00000
	v_lshl_add_u64 v[140:141], v[0:1], 0, s[0:1]
	s_mov_b64 s[0:1], 0xfd00000
	v_lshrrev_b32_e32 v4, 6, v114
	v_lshrrev_b32_e32 v5, 6, v115
	v_lshl_add_u64 v[142:143], v[0:1], 0, s[0:1]
	v_and_b32_e32 v0, 0x3f0, v123
	v_lshlrev_b32_e32 v2, 1, v122
	v_and_b32_e32 v4, 0xfffffc, v4
	v_and_b32_e32 v5, 0xfffffc, v5
	v_lshlrev_b32_e32 v6, 8, v114
	v_add_u32_e32 v0, 0, v0
	v_lshlrev_b32_e32 v1, 10, v162
	v_add_u32_e32 v3, 0, v2
	v_add_lshl_u32 v4, v4, v163, 8
	v_add_lshl_u32 v5, v5, v163, 8
	v_and_b32_e32 v6, 0x3000, v6
	v_readlane_b32 s0, v254, 35
	s_or_b32 s16, s4, 0x100
	v_cmp_eq_u32_e64 s[46:47], 3, v162
	v_ashrrev_i32_e32 v236, 4, v115
	v_add3_u32 v237, s0, v6, v2
	v_add_u32_e32 v238, v0, v4
	v_add_u32_e32 v239, v0, v5
	v_add_u32_e32 v240, v3, v1
	v_readlane_b32 s21, v251, 0
	s_branch .LBB0_1875
